# third conversion loop default-policy stores + hoisted norm-weight loads in the conversion items
# baseline (speedup 1.0000x reference)
; __device__ __forceinline__ void transpose_item(const float* W, int K, int N, bf16* WT, const float* scale, LAS float* scr, int item, int lane) {
;     const int nblk = N / 32, kb = item / nblk, nb = item % nblk, k0 = 64 * kb, n0 = 32 * nb;
;     {
;         const int q = lane & 7, r = lane >> 3;
;         f32x4 v[8];
; #pragma unroll
;         for (int i = 0; i < 8; ++i) v[i] = *(const f32x4*)(W + (size_t)(k0 + 8 * i + r) * N + n0 + 4 * q);
; #pragma unroll
;         for (int i = 0; i < 8; ++i) { const int kk = 8 * i + r; f32x4 x = v[i]; if (scale) x = x * scale[k0 + kk];
;             scr[kk * 33 + 4 * q + 0] = x[0]; scr[kk * 33 + 4 * q + 1] = x[1]; scr[kk * 33 + 4 * q + 2] = x[2]; scr[kk * 33 + 4 * q + 3] = x[3]; }
.LBB0_1270:
	s_mul_hi_i32 s2, s8, 0x2aaaaaab
	s_lshr_b32 s3, s2, 31
	s_ashr_i32 s2, s2, 4
	s_add_i32 s2, s2, s3
	s_lshl_b32 s4, s2, 6
	s_mulk_i32 s2, 0xf400
	s_add_i32 s2, s6, s2
	s_ashr_i32 s3, s2, 31
	s_waitcnt vmcnt(1)
	v_or_b32_e32 v48, s4, v1
	v_lshl_add_u64 v[2:3], s[2:3], 2, v[22:23]
	v_mad_i64_i32 v[4:5], s[10:11], v48, s14, v[2:3]
	global_load_dwordx4 v[36:39], v[4:5], off nt
	v_or_b32_e32 v4, 8, v48
	v_mad_i64_i32 v[4:5], s[10:11], v4, s14, v[2:3]
	global_load_dwordx4 v[40:43], v[4:5], off nt
	v_or_b32_e32 v4, 16, v48
	v_mad_i64_i32 v[4:5], s[10:11], v4, s14, v[2:3]
	global_load_dwordx4 v[44:47], v[4:5], off nt
	v_or_b32_e32 v4, 24, v48
	v_mad_i64_i32 v[4:5], s[10:11], v4, s14, v[2:3]
	global_load_dwordx4 v[18:21], v[4:5], off nt
	v_or_b32_e32 v4, 32, v48
	v_mad_i64_i32 v[4:5], s[10:11], v4, s14, v[2:3]
	global_load_dwordx4 v[14:17], v[4:5], off nt
	v_or_b32_e32 v4, 40, v48
	v_mad_i64_i32 v[4:5], s[10:11], v4, s14, v[2:3]
	global_load_dwordx4 v[10:13], v[4:5], off nt
	v_or_b32_e32 v4, 48, v48
	v_ashrrev_i32_e32 v49, 31, v48
	v_mad_i64_i32 v[4:5], s[10:11], v4, s14, v[2:3]
	global_load_dwordx4 v[6:9], v[4:5], off nt
	v_or_b32_e32 v4, 56, v48
	v_lshl_add_u64 v[48:49], v[48:49], 2, s[12:13]
	global_load_dword v48, v[48:49], off
	v_mad_i64_i32 v[2:3], s[10:11], v4, s14, v[2:3]
	global_load_dwordx4 v[2:5], v[2:3], off nt
	v_or_b32_e32 v202, s4, v26
	v_ashrrev_i32_e32 v203, 31, v202
	v_lshl_add_u64 v[202:203], v[202:203], 2, s[12:13]
	global_load_dword v221, v[202:203], off
	v_or_b32_e32 v204, s4, v27
	v_ashrrev_i32_e32 v205, 31, v204
	v_lshl_add_u64 v[204:205], v[204:205], 2, s[12:13]
	global_load_dword v222, v[204:205], off
	v_or_b32_e32 v206, s4, v28
	v_ashrrev_i32_e32 v207, 31, v206
	v_lshl_add_u64 v[206:207], v[206:207], 2, s[12:13]
	global_load_dword v223, v[206:207], off
	v_or_b32_e32 v208, s4, v29
	v_ashrrev_i32_e32 v209, 31, v208
	v_lshl_add_u64 v[208:209], v[208:209], 2, s[12:13]
	global_load_dword v224, v[208:209], off
	v_or_b32_e32 v210, s4, v30
	v_ashrrev_i32_e32 v211, 31, v210
	v_lshl_add_u64 v[210:211], v[210:211], 2, s[12:13]
	global_load_dword v225, v[210:211], off
	v_or_b32_e32 v212, s4, v31
	v_ashrrev_i32_e32 v213, 31, v212
	v_lshl_add_u64 v[212:213], v[212:213], 2, s[12:13]
	global_load_dword v226, v[212:213], off
	v_or_b32_e32 v214, s4, v32
	v_ashrrev_i32_e32 v215, 31, v214
	v_lshl_add_u64 v[214:215], v[214:215], 2, s[12:13]
	global_load_dword v227, v[214:215], off
	v_add_u32_e32 v35, 0x420, v34
	s_ashr_i32 s5, s4, 31
	s_add_i32 s8, s8, s9
	s_add_i32 s6, s6, s7
	s_cmpk_lt_i32 s8, 0x600
	s_waitcnt vmcnt(8)
	v_pk_mul_f32 v[36:37], v[36:37], v[48:49] op_sel_hi:[1,0]
	v_pk_mul_f32 v[38:39], v[38:39], v[48:49] op_sel_hi:[1,0]
	ds_write2_b32 v34, v36, v37 offset1:1
	ds_write2_b32 v34, v38, v39 offset0:2 offset1:3
	v_or_b32_e32 v36, s4, v26
	v_ashrrev_i32_e32 v37, 31, v36
	v_lshl_add_u64 v[36:37], v[36:37], 2, s[12:13]
	s_waitcnt vmcnt(6)
	v_mov_b32_e32 v36, v221
	s_waitcnt vmcnt(0)
	v_pk_mul_f32 v[38:39], v[42:43], v[36:37] op_sel_hi:[1,0]
	v_pk_mul_f32 v[36:37], v[40:41], v[36:37] op_sel_hi:[1,0]
	ds_write2_b32 v35, v36, v37 offset1:1
	v_or_b32_e32 v36, s4, v27
	v_ashrrev_i32_e32 v37, 31, v36
	v_lshl_add_u64 v[36:37], v[36:37], 2, s[12:13]
	s_waitcnt vmcnt(5)
	v_mov_b32_e32 v36, v222
	v_add_u32_e32 v35, 0x428, v34
	ds_write2_b32 v35, v38, v39 offset1:1
	v_add_u32_e32 v35, 0x840, v34
	s_waitcnt vmcnt(0)
	v_pk_mul_f32 v[38:39], v[46:47], v[36:37] op_sel_hi:[1,0]
	v_pk_mul_f32 v[36:37], v[44:45], v[36:37] op_sel_hi:[1,0]
	ds_write2_b32 v35, v36, v37 offset1:1
	v_or_b32_e32 v36, s4, v28
	v_ashrrev_i32_e32 v37, 31, v36
	v_lshl_add_u64 v[36:37], v[36:37], 2, s[12:13]
	s_waitcnt vmcnt(4)
	v_mov_b32_e32 v36, v223
	v_add_u32_e32 v35, 0x848, v34
	ds_write2_b32 v35, v38, v39 offset1:1
	v_add_u32_e32 v35, 0xc60, v34
	v_add_u32_e32 v38, s2, v1
	v_ashrrev_i32_e32 v39, 31, v38
	v_lshlrev_b64 v[40:41], 11, v[38:39]
	s_waitcnt vmcnt(0)
; #define LAS __attribute__((address_space(3)))
; __device__ __forceinline__ unsigned pk2(float lo, float hi) { f32x2_t v = {lo, hi}; bf16x2_t b = __builtin_convertvector(v, bf16x2_t); return __builtin_bit_cast(unsigned, b); }
; __device__ __forceinline__ void transpose_item(const float* W, int K, int N, bf16* WT, const float* scale, LAS float* scr, int item, int lane) {
;     ...
;         for (int i = 0; i < 8; ++i) { const int kk = 8 * i + r; f32x4 x = v[i]; if (scale) x = x * scale[k0 + kk];
;             scr[kk * 33 + 4 * q + 0] = x[0]; scr[kk * 33 + 4 * q + 1] = x[1]; scr[kk * 33 + 4 * q + 2] = x[2]; scr[kk * 33 + 4 * q + 3] = x[3]; }
;     }
;     asm volatile("s_waitcnt lgkmcnt(0)" ::: "memory");
;     const int c = lane & 7;
; #pragma unroll
;     for (int j = 0; j < 4; ++j) { const int n = (lane >> 3) + 8 * j; const LAS float* s = scr + (8 * c) * 33 + n;
;         v4u o; o.x = pk2(s[0 * 33], s[1 * 33]); o.y = pk2(s[2 * 33], s[3 * 33]); o.z = pk2(s[4 * 33], s[5 * 33]); o.w = pk2(s[6 * 33], s[7 * 33]);
;         *(v4u*)(WT + (size_t)(n0 + n) * K + k0 + 8 * c) = o; }
	v_pk_mul_f32 v[18:19], v[18:19], v[36:37] op_sel_hi:[1,0]
	v_pk_mul_f32 v[20:21], v[20:21], v[36:37] op_sel_hi:[1,0]
	ds_write2_b32 v35, v18, v19 offset1:1
	v_add_u32_e32 v18, 0xc68, v34
	ds_write2_b32 v18, v20, v21 offset1:1
	v_or_b32_e32 v18, s4, v29
	v_ashrrev_i32_e32 v19, 31, v18
	v_lshl_add_u64 v[18:19], v[18:19], 2, s[12:13]
	s_waitcnt vmcnt(3)
	v_mov_b32_e32 v18, v224
	s_waitcnt vmcnt(0)
	v_pk_mul_f32 v[16:17], v[16:17], v[18:19] op_sel_hi:[1,0]
	v_pk_mul_f32 v[14:15], v[14:15], v[18:19] op_sel_hi:[1,0]
	v_add_u32_e32 v18, 0x1080, v34
	ds_write2_b32 v18, v14, v15 offset1:1
	v_add_u32_e32 v14, 0x1088, v34
	ds_write2_b32 v14, v16, v17 offset1:1
	v_or_b32_e32 v14, s4, v30
	v_ashrrev_i32_e32 v15, 31, v14
	v_lshl_add_u64 v[14:15], v[14:15], 2, s[12:13]
	s_waitcnt vmcnt(2)
	v_mov_b32_e32 v14, v225
	s_waitcnt vmcnt(0)
	v_pk_mul_f32 v[12:13], v[12:13], v[14:15] op_sel_hi:[1,0]
	v_pk_mul_f32 v[10:11], v[10:11], v[14:15] op_sel_hi:[1,0]
	v_add_u32_e32 v14, 0x14a0, v34
	ds_write2_b32 v14, v10, v11 offset1:1
	v_add_u32_e32 v10, 0x14a8, v34
	ds_write2_b32 v10, v12, v13 offset1:1
	v_or_b32_e32 v10, s4, v31
	v_ashrrev_i32_e32 v11, 31, v10
	v_lshl_add_u64 v[10:11], v[10:11], 2, s[12:13]
	s_waitcnt vmcnt(1)
	v_mov_b32_e32 v10, v226
	s_waitcnt vmcnt(0)
	v_pk_mul_f32 v[8:9], v[8:9], v[10:11] op_sel_hi:[1,0]
	v_pk_mul_f32 v[6:7], v[6:7], v[10:11] op_sel_hi:[1,0]
	v_add_u32_e32 v10, 0x18c0, v34
	ds_write2_b32 v10, v6, v7 offset1:1
	v_add_u32_e32 v6, 0x18c8, v34
	ds_write2_b32 v6, v8, v9 offset1:1
	v_or_b32_e32 v6, s4, v32
	v_ashrrev_i32_e32 v7, 31, v6
	v_lshl_add_u64 v[6:7], v[6:7], 2, s[12:13]
	s_waitcnt vmcnt(0)
	v_mov_b32_e32 v6, v227
	s_waitcnt vmcnt(0)
	v_pk_mul_f32 v[4:5], v[4:5], v[6:7] op_sel_hi:[1,0]
	v_pk_mul_f32 v[2:3], v[2:3], v[6:7] op_sel_hi:[1,0]
	v_add_u32_e32 v6, 0x1ce0, v34
	ds_write2_b32 v6, v2, v3 offset1:1
	v_add_u32_e32 v2, 0x1ce8, v34
	ds_write2_b32 v2, v4, v5 offset1:1
	s_waitcnt lgkmcnt(0)
	ds_read2_b32 v[8:9], v33 offset0:33 offset1:41
	ds_read2_b32 v[10:11], v33 offset1:8
	ds_read2_b32 v[12:13], v33 offset0:66 offset1:74
	ds_read2_b32 v[14:15], v33 offset0:99 offset1:107
	ds_read2_b32 v[16:17], v33 offset0:132 offset1:140
	ds_read2_b32 v[18:19], v33 offset0:165 offset1:173
	ds_read2_b32 v[20:21], v33 offset0:198 offset1:206
	ds_read2_b32 v[36:37], v33 offset0:231 offset1:239
	v_lshl_add_u64 v[6:7], s[4:5], 1, v[24:25]
	s_waitcnt lgkmcnt(6)
	v_cvt_pk_bf16_f32 v2, v10, v8
	s_waitcnt lgkmcnt(4)
	v_cvt_pk_bf16_f32 v3, v12, v14
	s_waitcnt lgkmcnt(2)
	v_cvt_pk_bf16_f32 v4, v16, v18
	s_waitcnt lgkmcnt(0)
	v_cvt_pk_bf16_f32 v5, v20, v36
	v_lshl_add_u64 v[40:41], v[6:7], 0, v[40:41]
	v_add_u32_e32 v8, 8, v38
	global_store_dwordx4 v[40:41], v[2:5], off
	v_add_u32_e32 v40, 16, v38
	v_ashrrev_i32_e32 v41, 31, v40
	v_cvt_pk_bf16_f32 v2, v11, v9
	v_ashrrev_i32_e32 v9, 31, v8
	v_lshlrev_b64 v[8:9], 11, v[8:9]
	v_cvt_pk_bf16_f32 v3, v13, v15
	v_cvt_pk_bf16_f32 v4, v17, v19
	v_cvt_pk_bf16_f32 v5, v21, v37
	v_lshl_add_u64 v[8:9], v[6:7], 0, v[8:9]
	global_store_dwordx4 v[8:9], v[2:5], off
	ds_read2_b32 v[8:9], v33 offset0:49 offset1:57
	ds_read2_b32 v[10:11], v33 offset0:16 offset1:24
	ds_read2_b32 v[12:13], v33 offset0:82 offset1:90
	ds_read2_b32 v[14:15], v33 offset0:115 offset1:123
	ds_read2_b32 v[16:17], v33 offset0:148 offset1:156
	ds_read2_b32 v[18:19], v33 offset0:181 offset1:189
	ds_read2_b32 v[20:21], v33 offset0:214 offset1:222
	ds_read2_b32 v[36:37], v33 offset0:247 offset1:255
	v_lshlrev_b64 v[40:41], 11, v[40:41]
	s_waitcnt lgkmcnt(6)
	v_cvt_pk_bf16_f32 v2, v10, v8
	s_waitcnt lgkmcnt(4)
	v_cvt_pk_bf16_f32 v3, v12, v14
	s_waitcnt lgkmcnt(2)
	v_cvt_pk_bf16_f32 v4, v16, v18
	s_waitcnt lgkmcnt(0)
	v_cvt_pk_bf16_f32 v5, v20, v36
	v_lshl_add_u64 v[40:41], v[6:7], 0, v[40:41]
	v_add_u32_e32 v8, 24, v38
	global_store_dwordx4 v[40:41], v[2:5], off
	s_nop 1
	v_cvt_pk_bf16_f32 v2, v11, v9
	v_ashrrev_i32_e32 v9, 31, v8
	v_lshlrev_b64 v[8:9], 11, v[8:9]
	v_cvt_pk_bf16_f32 v3, v13, v15
	v_cvt_pk_bf16_f32 v4, v17, v19
	v_cvt_pk_bf16_f32 v5, v21, v37
	v_lshl_add_u64 v[6:7], v[6:7], 0, v[8:9]
	global_store_dwordx4 v[6:7], v[2:5], off
	s_waitcnt lgkmcnt(0)
	s_cbranch_scc1 .LBB0_1270
	v_readlane_b32 s50, v255, 24
	v_readlane_b32 s51, v255, 25
